# GU GEMM: row-rstd table prefetched and computed inside the last K iteration (waves 0-3), epilogue no longer loads/waits/barriers for it
# speedup vs baseline: 1.0161x; 1.0075x over previous
; #define PG8_LAS __attribute__((address_space(3)))
; #define PG8_STAGE(bufoff, gbase, voff) do { _Pragma("unroll") for (int _i = 0; _i < 2; ++_i) \
;         __builtin_amdgcn_global_load_lds((const unsigned*)((const char*)(gbase) + (voff)[_i]), (PG8_LAS unsigned*)(lds + (bufoff) + ldsw + _i * 8192), 16, 0, 0); } while (0)
; #define PG8_LDA(dst, b, h) do { _Pragma("unroll") for (int m = 0; m < 4; ++m) _Pragma("unroll") for (int k = 0; k < 2; ++k) dst[m][k] = *(const PG8_LAS bf16x8*)(lds + PG8_SA(b, h) + aoff + m * 2048 + k * 1024); } while (0)
; #define PG8_LDB(dst, b, h) do { _Pragma("unroll") for (int n = 0; n < 2; ++n) _Pragma("unroll") for (int k = 0; k < 2; ++k) dst[n][k] = *(const PG8_LAS bf16x8*)(lds + PG8_SB(b, h) + boff + n * 2048 + k * 1024); } while (0)
; #define PG8_WAIT_V(n) asm volatile("s_waitcnt vmcnt(" #n ")" ::: "memory")
; #define PG8_WAIT_L(n) asm volatile("s_waitcnt lgkmcnt(" #n ")" ::: "memory")
; __device__ __forceinline__ PG8_LAS const float* stage_rstd(const float* PS, PG8_LAS unsigned char* lds, int pm) {
;     int t = threadIdx.x; asm volatile("" : "+v"(t));
;     PG8_LAS float* R = (PG8_LAS float*)(lds + 131072);
;     if (t < 256) R[t] = row_rstd(PS + (size_t)(pm * BM + t) * 16);
; template <class Epi, class Sched, bool ALIGN_EPI = false, bool SP2 = false>
; __device__ __forceinline__ void gemm_phase(PG8_LAS unsigned char* lds, const Gemm g, const Sched& S, const Epi& E) {
;     ...
;         for (int t = 0; t < nt; t += 2) {
;             const bool last = (t == nt - 2);
;             const char* a1 = cA + (size_t)(t + 1) * kstep;
;             const char* a2 = last ? nA : cA + (size_t)(t + 2) * kstep; const char* b2 = last ? nB : cB + (size_t)(t + 2) * kstep;
;             const char* a3 = a2 + kstep; const char* b3 = b2 + kstep;
;             if (last && has_next) S.a_ready(nxt);
;             if constexpr (SP2) {
;             PG8_LDB(B0, 0, 0); PG8_LDB(B1, 0, 1); PG8_SCHED; PG8_LDA(At, 0, 0); PG8_STAGE(PG8_SA(1, 1), a1 + hstep, voffA);
;             PG8_WAIT_V(8); PG8_WAIT_L(0); PG8_BAR; PG8_MMA(0, 0, At, B0); PG8_MMA(0, 1, At, B1); PG8_BAR; PG8_SCHED;
;             PG8_LDA(At, 0, 1); PG8_STAGE(PG8_SB(0, 0), b2, voffB); PG8_STAGE(PG8_SB(0, 1), b2 + hstep, voffB); PG8_STAGE(PG8_SA(0, 0), a2, voffA);
;             PG8_WAIT_V(8); PG8_WAIT_L(0); PG8_BAR; PG8_MMA(1, 0, At, B0); PG8_MMA(1, 1, At, B1); PG8_BAR; PG8_SCHED;
.LBB0_35:
	s_add_u32 s24, s0, 0xfffc0080
	s_addc_u32 s25, s1, -1
	s_add_i32 s52, 0, 0x10000
	s_cmp_eq_u32 s51, 12
	s_cselect_b32 s27, s4, s25
	s_cselect_b32 s26, s5, s24
	s_cselect_b32 s25, s3, s50
	s_cselect_b32 s24, s19, s49
	s_cmp_eq_u32 s51, 12
	s_cbranch_scc0 .Lrs_gu_a
	s_cmp_lt_u32 s39, 0x1000
	s_cbranch_scc0 .Lrs_gu_a
	s_lshl_b32 s98, s48, 8
	v_add_u32_e32 v250, s98, v216
	v_lshlrev_b32_e32 v250, 6, v250
	global_load_dwordx4 v[236:239], v250, s[14:15]
	global_load_dwordx4 v[240:243], v250, s[14:15] offset:16
	global_load_dwordx4 v[244:247], v250, s[14:15] offset:32
	global_load_dwordx2 v[248:249], v250, s[14:15] offset:48
	global_load_dwordx2 v[190:191], v250, s[14:15] offset:56
.Lrs_gu_a:
	s_add_i32 s54, 0, 0x14000
	v_add_u32_e32 v156, s52, v141
	v_add_u32_e32 v172, s54, v141
	ds_read_b128 v[144:147], v156
	ds_read_b128 v[148:151], v156 offset:1024
	ds_read_b128 v[152:155], v156 offset:2048
	ds_read_b128 v[156:159], v156 offset:3072
	ds_read_b128 v[160:163], v172
	ds_read_b128 v[164:167], v172 offset:1024
	ds_read_b128 v[168:171], v172 offset:2048
	ds_read_b128 v[172:175], v172 offset:3072
	v_lshl_add_u64 v[214:215], s[0:1], 0, v[136:137]
	s_add_i32 m0, s40, 0xc000
	ds_read_b128 v[176:179], v143
	ds_read_b128 v[180:183], v143 offset:1024
	ds_read_b128 v[194:197], v143 offset:2048
	ds_read_b128 v[198:201], v143 offset:3072
	ds_read_b128 v[202:205], v143 offset:4096
	ds_read_b128 v[206:209], v143 offset:5120
	ds_read_b128 v[210:213], v143 offset:6144
	ds_read_b128 v[228:231], v143 offset:7168
	global_load_lds_dwordx4 v[214:215], off
	v_lshl_add_u64 v[214:215], s[0:1], 0, v[138:139]
	s_add_i32 m0, s40, 0xe000
	s_nop 0
	global_load_lds_dwordx4 v[214:215], off
	s_waitcnt vmcnt(8)
	s_waitcnt lgkmcnt(0)
	s_barrier
	s_setprio 1
	s_waitcnt lgkmcnt(0)
	v_mfma_f32_16x16x32_bf16 v[124:127], v[144:147], v[176:179], v[124:127]
	v_mfma_f32_16x16x32_bf16 v[116:119], v[152:155], v[176:179], v[116:119]
	v_mfma_f32_16x16x32_bf16 v[108:111], v[144:147], v[194:197], v[108:111]
	v_mfma_f32_16x16x32_bf16 v[100:103], v[152:155], v[194:197], v[100:103]
	v_mfma_f32_16x16x32_bf16 v[92:95], v[144:147], v[202:205], v[92:95]
	v_mfma_f32_16x16x32_bf16 v[84:87], v[152:155], v[202:205], v[84:87]
	v_mfma_f32_16x16x32_bf16 v[76:79], v[144:147], v[210:213], v[76:79]
	v_mfma_f32_16x16x32_bf16 v[68:71], v[152:155], v[210:213], v[68:71]
	v_mfma_f32_16x16x32_bf16 v[124:127], v[148:151], v[180:183], v[124:127]
	v_mfma_f32_16x16x32_bf16 v[116:119], v[156:159], v[180:183], v[116:119]
	v_mfma_f32_16x16x32_bf16 v[108:111], v[148:151], v[198:201], v[108:111]
	v_mfma_f32_16x16x32_bf16 v[100:103], v[156:159], v[198:201], v[100:103]
	v_mfma_f32_16x16x32_bf16 v[92:95], v[148:151], v[206:209], v[92:95]
	v_mfma_f32_16x16x32_bf16 v[84:87], v[156:159], v[206:209], v[84:87]
	v_mfma_f32_16x16x32_bf16 v[76:79], v[148:151], v[228:231], v[76:79]
	v_mfma_f32_16x16x32_bf16 v[68:71], v[156:159], v[228:231], v[68:71]
	s_setprio 0
	s_setprio 1
	v_mfma_f32_16x16x32_bf16 v[120:123], v[160:163], v[176:179], v[120:123]
	v_mfma_f32_16x16x32_bf16 v[112:115], v[168:171], v[176:179], v[112:115]
	v_mfma_f32_16x16x32_bf16 v[104:107], v[160:163], v[194:197], v[104:107]
	v_mfma_f32_16x16x32_bf16 v[96:99], v[168:171], v[194:197], v[96:99]
	v_mfma_f32_16x16x32_bf16 v[88:91], v[160:163], v[202:205], v[88:91]
	v_mfma_f32_16x16x32_bf16 v[80:83], v[168:171], v[202:205], v[80:83]
	v_mfma_f32_16x16x32_bf16 v[72:75], v[160:163], v[210:213], v[72:75]
	v_mfma_f32_16x16x32_bf16 v[64:67], v[168:171], v[210:213], v[64:67]
	v_mfma_f32_16x16x32_bf16 v[120:123], v[164:167], v[180:183], v[120:123]
	v_mfma_f32_16x16x32_bf16 v[112:115], v[172:175], v[180:183], v[112:115]
	v_mfma_f32_16x16x32_bf16 v[104:107], v[164:167], v[198:201], v[104:107]
	v_mfma_f32_16x16x32_bf16 v[96:99], v[172:175], v[198:201], v[96:99]
	v_mfma_f32_16x16x32_bf16 v[88:91], v[164:167], v[206:209], v[88:91]
	v_mfma_f32_16x16x32_bf16 v[80:83], v[172:175], v[206:209], v[80:83]
	v_mfma_f32_16x16x32_bf16 v[72:75], v[164:167], v[228:231], v[72:75]
	v_mfma_f32_16x16x32_bf16 v[64:67], v[172:175], v[228:231], v[64:67]
	s_setprio 0
	s_barrier
	s_add_i32 s52, s52, s39
	v_lshl_add_u64 v[214:215], s[24:25], 0, v[132:133]
	s_mov_b32 m0, s52
	ds_read_b128 v[176:179], v143 offset:16384
	ds_read_b128 v[180:183], v143 offset:17408
	ds_read_b128 v[194:197], v143 offset:18432
	ds_read_b128 v[198:201], v143 offset:19456
	ds_read_b128 v[202:205], v143 offset:20480
	ds_read_b128 v[206:209], v143 offset:21504
	ds_read_b128 v[210:213], v143 offset:22528
	ds_read_b128 v[228:231], v143 offset:23552
	global_load_lds_dwordx4 v[214:215], off
	s_add_i32 m0, s52, 0x2000
	s_add_u32 s52, s24, 0x40000
	v_lshl_add_u64 v[224:225], s[24:25], 0, v[128:129]
	s_addc_u32 s53, s25, 0
	s_add_i32 s54, s54, s39
	global_load_lds_dwordx4 v[224:225], off
	v_lshl_add_u64 v[226:227], s[52:53], 0, v[132:133]
	s_mov_b32 m0, s54
	v_lshl_add_u64 v[232:233], s[26:27], 0, v[130:131]
	global_load_lds_dwordx4 v[226:227], off
	v_lshl_add_u64 v[226:227], s[52:53], 0, v[128:129]
	s_add_i32 m0, s54, 0x2000
	s_nop 0
	global_load_lds_dwordx4 v[226:227], off
	v_lshl_add_u64 v[226:227], s[26:27], 0, v[134:135]
	s_mov_b32 m0, s40
	s_nop 0
	global_load_lds_dwordx4 v[226:227], off
	s_mov_b32 m0, s41
	s_nop 0
	global_load_lds_dwordx4 v[232:233], off
	s_waitcnt vmcnt(8)
	s_waitcnt lgkmcnt(0)
	s_barrier
; #define PG8_LAS __attribute__((address_space(3)))
; __device__ __forceinline__ unsigned cvt_pk_bf16(float lo, float hi) { unsigned r; asm volatile("v_cvt_pk_bf16_f32 %0, %1, %2" : "=v"(r) : "v"(lo), "v"(hi)); return r; }
; __device__ __forceinline__ float sum4(const f32x4 a) { return (a[0] + a[1]) + (a[2] + a[3]); }
; #define PG8_STAGE(bufoff, gbase, voff) do { _Pragma("unroll") for (int _i = 0; _i < 2; ++_i) \
;         __builtin_amdgcn_global_load_lds((const unsigned*)((const char*)(gbase) + (voff)[_i]), (PG8_LAS unsigned*)(lds + (bufoff) + ldsw + _i * 8192), 16, 0, 0); } while (0)
; __device__ __forceinline__ float row_rstd(const float* ps_row) {
;     const f32x4* p = (const f32x4*)ps_row; const f32x4 a = p[0], b = p[1], c = p[2], d = p[3];
;     const float s = (sum4(a) + sum4(b)) + (sum4(c) + sum4(d));
;     return 1.0f / sqrtf(s * (1.0f / 1024.0f) + E_EPS);
; }
; __device__ __forceinline__ u32x4 pack8(const f32x4 a, const f32x4 b) { u32x4 w; w.x = cvt_pk_bf16(a[0], a[1]); w.y = cvt_pk_bf16(a[2], a[3]); w.z = cvt_pk_bf16(b[0], b[1]); w.w = cvt_pk_bf16(b[2], b[3]); return w; }
; __device__ __forceinline__ bf16_t f2bf1(float f) { return (bf16_t)(cvt_pk_bf16(f, 0.f) & 0xffffu); }
; __device__ __forceinline__ PG8_LAS const float* stage_rstd(const float* PS, PG8_LAS unsigned char* lds, int pm) {
;     int t = threadIdx.x; asm volatile("" : "+v"(t));
;     PG8_LAS float* R = (PG8_LAS float*)(lds + 131072);
;     if (t < 256) R[t] = row_rstd(PS + (size_t)(pm * BM + t) * 16);
; template <class Epi, class Sched, bool ALIGN_EPI = false, bool SP2 = false>
; __device__ __forceinline__ void gemm_phase(PG8_LAS unsigned char* lds, const Gemm g, const Sched& S, const Epi& E) {
;     ...
;             if constexpr (SP2) {
;             PG8_LDB(B0, 0, 0); PG8_LDB(B1, 0, 1); PG8_SCHED; PG8_LDA(At, 0, 0); PG8_STAGE(PG8_SA(1, 1), a1 + hstep, voffA);
;             PG8_WAIT_V(8); PG8_WAIT_L(0); PG8_BAR; PG8_MMA(0, 0, At, B0); PG8_MMA(0, 1, At, B1); PG8_BAR; PG8_SCHED;
;             PG8_LDA(At, 0, 1); PG8_STAGE(PG8_SB(0, 0), b2, voffB); PG8_STAGE(PG8_SB(0, 1), b2 + hstep, voffB); PG8_STAGE(PG8_SA(0, 0), a2, voffA);
;             PG8_WAIT_V(8); PG8_WAIT_L(0); PG8_BAR; PG8_MMA(1, 0, At, B0); PG8_MMA(1, 1, At, B1); PG8_BAR; PG8_SCHED;
;             PG8_LDB(B0, 1, 0); PG8_LDB(B1, 1, 1); PG8_SCHED; PG8_LDA(At, 1, 0); PG8_STAGE(PG8_SA(0, 1), a2 + hstep, voffA);
	s_setprio 1
	s_waitcnt lgkmcnt(0)
	v_mfma_f32_16x16x32_bf16 v[60:63], v[144:147], v[176:179], v[60:63]
	v_mfma_f32_16x16x32_bf16 v[52:55], v[152:155], v[176:179], v[52:55]
	v_mfma_f32_16x16x32_bf16 v[44:47], v[144:147], v[194:197], v[44:47]
	v_mfma_f32_16x16x32_bf16 v[36:39], v[152:155], v[194:197], v[36:39]
	v_mfma_f32_16x16x32_bf16 v[28:31], v[144:147], v[202:205], v[28:31]
	v_mfma_f32_16x16x32_bf16 v[20:23], v[152:155], v[202:205], v[20:23]
	v_mfma_f32_16x16x32_bf16 v[12:15], v[144:147], v[210:213], v[12:15]
	v_mfma_f32_16x16x32_bf16 v[4:7], v[152:155], v[210:213], v[4:7]
	v_mfma_f32_16x16x32_bf16 v[60:63], v[148:151], v[180:183], v[60:63]
	v_mfma_f32_16x16x32_bf16 v[52:55], v[156:159], v[180:183], v[52:55]
	v_mfma_f32_16x16x32_bf16 v[44:47], v[148:151], v[198:201], v[44:47]
	v_mfma_f32_16x16x32_bf16 v[36:39], v[156:159], v[198:201], v[36:39]
	v_mfma_f32_16x16x32_bf16 v[28:31], v[148:151], v[206:209], v[28:31]
	v_mfma_f32_16x16x32_bf16 v[20:23], v[156:159], v[206:209], v[20:23]
	v_mfma_f32_16x16x32_bf16 v[12:15], v[148:151], v[228:231], v[12:15]
	v_mfma_f32_16x16x32_bf16 v[4:7], v[156:159], v[228:231], v[4:7]
	s_setprio 0
	s_setprio 1
	v_mfma_f32_16x16x32_bf16 v[56:59], v[160:163], v[176:179], v[56:59]
	v_mfma_f32_16x16x32_bf16 v[48:51], v[168:171], v[176:179], v[48:51]
	v_mfma_f32_16x16x32_bf16 v[40:43], v[160:163], v[194:197], v[40:43]
	v_mfma_f32_16x16x32_bf16 v[32:35], v[168:171], v[194:197], v[32:35]
	v_mfma_f32_16x16x32_bf16 v[24:27], v[160:163], v[202:205], v[24:27]
	v_mfma_f32_16x16x32_bf16 v[16:19], v[168:171], v[202:205], v[16:19]
	v_mfma_f32_16x16x32_bf16 v[8:11], v[160:163], v[210:213], v[8:11]
	v_mfma_f32_16x16x32_bf16 v[0:3], v[168:171], v[210:213], v[0:3]
	v_mfma_f32_16x16x32_bf16 v[56:59], v[164:167], v[180:183], v[56:59]
	v_mfma_f32_16x16x32_bf16 v[48:51], v[172:175], v[180:183], v[48:51]
	v_mfma_f32_16x16x32_bf16 v[40:43], v[164:167], v[198:201], v[40:43]
	v_mfma_f32_16x16x32_bf16 v[32:35], v[172:175], v[198:201], v[32:35]
	v_mfma_f32_16x16x32_bf16 v[24:27], v[164:167], v[206:209], v[24:27]
	v_mfma_f32_16x16x32_bf16 v[16:19], v[172:175], v[206:209], v[16:19]
	v_mfma_f32_16x16x32_bf16 v[8:11], v[164:167], v[228:231], v[8:11]
	v_mfma_f32_16x16x32_bf16 v[0:3], v[172:175], v[228:231], v[0:3]
	s_setprio 0
	s_barrier
	s_add_i32 s52, 0, 0x18000
	s_add_i32 s53, 0, 0x1c000
	s_cmp_eq_u32 s51, 12
	s_cbranch_scc0 .Lrs_gu_b
	s_cmp_lt_u32 s39, 0x1000
	s_cbranch_scc0 .Lrs_gu_b
	v_add_f32_e32 v236, v236, v237
	v_add_f32_e32 v238, v238, v239
	v_add_f32_e32 v240, v240, v241
	v_add_f32_e32 v242, v242, v243
	v_add_f32_e32 v244, v244, v245
	v_add_f32_e32 v246, v246, v247
	v_add_f32_e32 v248, v248, v249
	v_add_f32_e32 v190, v190, v191
	v_add_f32_e32 v236, v236, v238
	v_add_f32_e32 v240, v240, v242
	v_add_f32_e32 v244, v244, v246
	v_add_f32_e32 v248, v248, v190
	v_add_f32_e32 v236, v236, v240
	v_add_f32_e32 v244, v244, v248
	v_add_f32_e32 v237, v236, v244
	s_mov_b32 s98, 0xf800000
	v_fmamk_f32 v237, v237, 0x3a800000, v218
	v_mul_f32_e32 v238, 0x4f800000, v237
	v_cmp_gt_f32_e32 vcc, s98, v237
	s_nop 1
	v_cndmask_b32_e32 v237, v237, v238, vcc
	v_sqrt_f32_e32 v238, v237
	s_nop 0
	v_add_u32_e32 v239, -1, v238
	v_add_u32_e32 v240, 1, v238
	v_fma_f32 v241, -v239, v238, v237
	v_fma_f32 v242, -v240, v238, v237
	v_cmp_ge_f32_e64 s[98:99], 0, v241
	s_nop 1
	v_cndmask_b32_e64 v238, v238, v239, s[98:99]
	v_cmp_lt_f32_e64 s[98:99], 0, v242
	s_nop 1
	v_cndmask_b32_e64 v238, v238, v240, s[98:99]
	v_mul_f32_e32 v239, 0x37800000, v238
	v_cndmask_b32_e32 v238, v238, v239, vcc
	v_cmp_class_f32_e32 vcc, v237, v219
	s_nop 1
	v_cndmask_b32_e32 v237, v238, v237, vcc
	v_div_scale_f32 v238, s[98:99], v237, v237, 1.0
	v_rcp_f32_e32 v239, v238
	v_div_scale_f32 v240, vcc, 1.0, v237, 1.0
	v_fma_f32 v241, -v238, v239, 1.0
	v_fmac_f32_e32 v239, v241, v239
	v_mul_f32_e32 v241, v240, v239
	v_fma_f32 v242, -v238, v241, v240
	v_fmac_f32_e32 v241, v242, v239
	v_fma_f32 v238, -v238, v241, v240
	v_div_fmas_f32 v238, v238, v239, v241
	v_div_fixup_f32 v237, v238, v237, 1.0
	v_lshl_add_u32 v250, v216, 2, 0
	v_add_u32_e32 v250, 0x20000, v250
	ds_write_b32 v250, v237
.Lrs_gu_b:
	v_add_u32_e32 v156, s52, v141
	v_add_u32_e32 v172, s53, v141
	ds_read_b128 v[144:147], v156
	ds_read_b128 v[148:151], v156 offset:1024
	ds_read_b128 v[152:155], v156 offset:2048
	ds_read_b128 v[156:159], v156 offset:3072
	ds_read_b128 v[160:163], v172
	ds_read_b128 v[164:167], v172 offset:1024
	ds_read_b128 v[168:171], v172 offset:2048
	ds_read_b128 v[172:175], v172 offset:3072
	s_add_u32 s26, s26, 0x40000
	s_addc_u32 s27, s27, 0
	s_mov_b32 m0, s42
	v_lshl_add_u64 v[234:235], s[26:27], 0, v[134:135]
	ds_read_b128 v[176:179], v143 offset:32768
	ds_read_b128 v[180:183], v143 offset:33792
	ds_read_b128 v[194:197], v143 offset:34816
	ds_read_b128 v[198:201], v143 offset:35840
	ds_read_b128 v[202:205], v143 offset:36864
	ds_read_b128 v[206:209], v143 offset:37888
	ds_read_b128 v[210:213], v143 offset:38912
	ds_read_b128 v[228:231], v143 offset:39936
	global_load_lds_dwordx4 v[234:235], off
	v_lshl_add_u64 v[234:235], s[26:27], 0, v[130:131]
	s_mov_b32 m0, s43
	s_nop 0
	global_load_lds_dwordx4 v[234:235], off
	s_waitcnt vmcnt(8)
	s_waitcnt lgkmcnt(0)
	s_barrier
; #define PG8_STAGE(bufoff, gbase, voff) do { _Pragma("unroll") for (int _i = 0; _i < 2; ++_i) \
;         __builtin_amdgcn_global_load_lds((const unsigned*)((const char*)(gbase) + (voff)[_i]), (PG8_LAS unsigned*)(lds + (bufoff) + ldsw + _i * 8192), 16, 0, 0); } while (0)
; #define PG8_LDA(dst, b, h) do { _Pragma("unroll") for (int m = 0; m < 4; ++m) _Pragma("unroll") for (int k = 0; k < 2; ++k) dst[m][k] = *(const PG8_LAS bf16x8*)(lds + PG8_SA(b, h) + aoff + m * 2048 + k * 1024); } while (0)
; #define PG8_LDB(dst, b, h) do { _Pragma("unroll") for (int n = 0; n < 2; ++n) _Pragma("unroll") for (int k = 0; k < 2; ++k) dst[n][k] = *(const PG8_LAS bf16x8*)(lds + PG8_SB(b, h) + boff + n * 2048 + k * 1024); } while (0)
; #define PG8_MMA(ai, bj, At, Bt) do { __builtin_amdgcn_s_setprio(1); _Pragma("unroll") for (int m = 0; m < 4; ++m) _Pragma("unroll") for (int n = 0; n < 2; ++n) _Pragma("unroll") for (int k = 0; k < 2; ++k) \
;         acc[ai][bj][m][n] = __builtin_amdgcn_mfma_f32_16x16x32_bf16(Bt[n][k], At[m][k], acc[ai][bj][m][n], 0, 0, 0); __builtin_amdgcn_s_setprio(0); } while (0)
; #define PG8_WAIT_V(n) asm volatile("s_waitcnt vmcnt(" #n ")" ::: "memory")
; #define PG8_WAIT_L(n) asm volatile("s_waitcnt lgkmcnt(" #n ")" ::: "memory")
; #define PG8_BAR __builtin_amdgcn_s_barrier()
; template <class Epi, class Sched, bool ALIGN_EPI = false, bool SP2 = false>
; __device__ __forceinline__ void gemm_phase(PG8_LAS unsigned char* lds, const Gemm g, const Sched& S, const Epi& E) {
;     ...
;             PG8_WAIT_V(8); PG8_WAIT_L(0); PG8_BAR; PG8_MMA(0, 0, At, B0); PG8_MMA(0, 1, At, B1); PG8_BAR; PG8_SCHED;
;             PG8_LDA(At, 0, 1); PG8_STAGE(PG8_SB(0, 0), b2, voffB); PG8_STAGE(PG8_SB(0, 1), b2 + hstep, voffB); PG8_STAGE(PG8_SA(0, 0), a2, voffA);
;             PG8_WAIT_V(8); PG8_WAIT_L(0); PG8_BAR; PG8_MMA(1, 0, At, B0); PG8_MMA(1, 1, At, B1); PG8_BAR; PG8_SCHED;
;             PG8_LDB(B0, 1, 0); PG8_LDB(B1, 1, 1); PG8_SCHED; PG8_LDA(At, 1, 0); PG8_STAGE(PG8_SA(0, 1), a2 + hstep, voffA);
;             PG8_WAIT_V(8); PG8_WAIT_L(0); PG8_BAR; PG8_MMA(0, 0, At, B0); PG8_MMA(0, 1, At, B1); PG8_BAR; PG8_SCHED;
;             PG8_LDA(At, 1, 1); PG8_STAGE(PG8_SB(1, 0), b3, voffB); PG8_STAGE(PG8_SB(1, 1), b3 + hstep, voffB); PG8_STAGE(PG8_SA(1, 0), a3, voffA);
;             PG8_WAIT_V(8); PG8_WAIT_L(0); PG8_BAR; PG8_MMA(1, 0, At, B0); PG8_MMA(1, 1, At, B1); PG8_BAR; PG8_SCHED;
	s_setprio 1
	s_waitcnt lgkmcnt(0)
	v_mfma_f32_16x16x32_bf16 v[124:127], v[144:147], v[176:179], v[124:127]
	v_mfma_f32_16x16x32_bf16 v[116:119], v[152:155], v[176:179], v[116:119]
	v_mfma_f32_16x16x32_bf16 v[108:111], v[144:147], v[194:197], v[108:111]
	v_mfma_f32_16x16x32_bf16 v[100:103], v[152:155], v[194:197], v[100:103]
	v_mfma_f32_16x16x32_bf16 v[92:95], v[144:147], v[202:205], v[92:95]
	v_mfma_f32_16x16x32_bf16 v[84:87], v[152:155], v[202:205], v[84:87]
	v_mfma_f32_16x16x32_bf16 v[76:79], v[144:147], v[210:213], v[76:79]
	v_mfma_f32_16x16x32_bf16 v[68:71], v[152:155], v[210:213], v[68:71]
	v_mfma_f32_16x16x32_bf16 v[124:127], v[148:151], v[180:183], v[124:127]
	v_mfma_f32_16x16x32_bf16 v[116:119], v[156:159], v[180:183], v[116:119]
	v_mfma_f32_16x16x32_bf16 v[108:111], v[148:151], v[198:201], v[108:111]
	v_mfma_f32_16x16x32_bf16 v[100:103], v[156:159], v[198:201], v[100:103]
	v_mfma_f32_16x16x32_bf16 v[92:95], v[148:151], v[206:209], v[92:95]
	v_mfma_f32_16x16x32_bf16 v[84:87], v[156:159], v[206:209], v[84:87]
	v_mfma_f32_16x16x32_bf16 v[76:79], v[148:151], v[228:231], v[76:79]
	v_mfma_f32_16x16x32_bf16 v[68:71], v[156:159], v[228:231], v[68:71]
	s_setprio 0
	s_setprio 1
	v_mfma_f32_16x16x32_bf16 v[120:123], v[160:163], v[176:179], v[120:123]
	v_mfma_f32_16x16x32_bf16 v[112:115], v[168:171], v[176:179], v[112:115]
	v_mfma_f32_16x16x32_bf16 v[104:107], v[160:163], v[194:197], v[104:107]
	v_mfma_f32_16x16x32_bf16 v[96:99], v[168:171], v[194:197], v[96:99]
	v_mfma_f32_16x16x32_bf16 v[88:91], v[160:163], v[202:205], v[88:91]
	v_mfma_f32_16x16x32_bf16 v[80:83], v[168:171], v[202:205], v[80:83]
	v_mfma_f32_16x16x32_bf16 v[72:75], v[160:163], v[210:213], v[72:75]
	v_mfma_f32_16x16x32_bf16 v[64:67], v[168:171], v[210:213], v[64:67]
	v_mfma_f32_16x16x32_bf16 v[120:123], v[164:167], v[180:183], v[120:123]
	v_mfma_f32_16x16x32_bf16 v[112:115], v[172:175], v[180:183], v[112:115]
	v_mfma_f32_16x16x32_bf16 v[104:107], v[164:167], v[198:201], v[104:107]
	v_mfma_f32_16x16x32_bf16 v[96:99], v[172:175], v[198:201], v[96:99]
	v_mfma_f32_16x16x32_bf16 v[88:91], v[164:167], v[206:209], v[88:91]
	v_mfma_f32_16x16x32_bf16 v[80:83], v[172:175], v[206:209], v[80:83]
	v_mfma_f32_16x16x32_bf16 v[72:75], v[164:167], v[228:231], v[72:75]
	v_mfma_f32_16x16x32_bf16 v[64:67], v[172:175], v[228:231], v[64:67]
	s_setprio 0
	s_barrier
	s_add_i32 s26, s52, s39
	v_lshl_add_u64 v[214:215], v[214:215], 0, s[96:97]
	s_mov_b32 m0, s26
	ds_read_b128 v[176:179], v143 offset:49152
	ds_read_b128 v[180:183], v143 offset:50176
	ds_read_b128 v[194:197], v143 offset:51200
	ds_read_b128 v[198:201], v143 offset:52224
	ds_read_b128 v[202:205], v143 offset:53248
	ds_read_b128 v[206:209], v143 offset:54272
	ds_read_b128 v[210:213], v143 offset:55296
	ds_read_b128 v[228:231], v143 offset:56320
	global_load_lds_dwordx4 v[214:215], off
	s_add_i32 m0, s26, 0x2000
	s_add_u32 s24, s24, 0x40080
	v_lshl_add_u64 v[214:215], v[224:225], 0, s[96:97]
	s_addc_u32 s25, s25, 0
	s_add_i32 s26, s53, s39
	global_load_lds_dwordx4 v[214:215], off
	v_lshl_add_u64 v[214:215], s[24:25], 0, v[132:133]
	s_mov_b32 m0, s26
	s_nop 0
	global_load_lds_dwordx4 v[214:215], off
	v_lshl_add_u64 v[214:215], s[24:25], 0, v[128:129]
	s_add_i32 m0, s26, 0x2000
	s_nop 0
	global_load_lds_dwordx4 v[214:215], off
	v_lshl_add_u64 v[214:215], v[226:227], 0, s[96:97]
	s_mov_b32 m0, s44
	s_nop 0
	global_load_lds_dwordx4 v[214:215], off
	v_lshl_add_u64 v[214:215], v[232:233], 0, s[96:97]
	s_mov_b32 m0, s45
	s_nop 0
	global_load_lds_dwordx4 v[214:215], off
	s_waitcnt vmcnt(8)
	s_waitcnt lgkmcnt(0)
	s_barrier
	s_setprio 1
	s_waitcnt lgkmcnt(0)
	v_mfma_f32_16x16x32_bf16 v[60:63], v[144:147], v[176:179], v[60:63]
	v_mfma_f32_16x16x32_bf16 v[52:55], v[152:155], v[176:179], v[52:55]
	v_mfma_f32_16x16x32_bf16 v[44:47], v[144:147], v[194:197], v[44:47]
	v_mfma_f32_16x16x32_bf16 v[36:39], v[152:155], v[194:197], v[36:39]
	v_mfma_f32_16x16x32_bf16 v[28:31], v[144:147], v[202:205], v[28:31]
	v_mfma_f32_16x16x32_bf16 v[20:23], v[152:155], v[202:205], v[20:23]
	v_mfma_f32_16x16x32_bf16 v[12:15], v[144:147], v[210:213], v[12:15]
	v_mfma_f32_16x16x32_bf16 v[4:7], v[152:155], v[210:213], v[4:7]
	v_mfma_f32_16x16x32_bf16 v[60:63], v[148:151], v[180:183], v[60:63]
	v_mfma_f32_16x16x32_bf16 v[52:55], v[156:159], v[180:183], v[52:55]
	v_mfma_f32_16x16x32_bf16 v[44:47], v[148:151], v[198:201], v[44:47]
	v_mfma_f32_16x16x32_bf16 v[36:39], v[156:159], v[198:201], v[36:39]
	v_mfma_f32_16x16x32_bf16 v[28:31], v[148:151], v[206:209], v[28:31]
	v_mfma_f32_16x16x32_bf16 v[20:23], v[156:159], v[206:209], v[20:23]
	v_mfma_f32_16x16x32_bf16 v[12:15], v[148:151], v[228:231], v[12:15]
	v_mfma_f32_16x16x32_bf16 v[4:7], v[156:159], v[228:231], v[4:7]
	s_setprio 0
	s_setprio 1
	v_mfma_f32_16x16x32_bf16 v[56:59], v[160:163], v[176:179], v[56:59]
	v_mfma_f32_16x16x32_bf16 v[48:51], v[168:171], v[176:179], v[48:51]
	v_mfma_f32_16x16x32_bf16 v[40:43], v[160:163], v[194:197], v[40:43]
	v_mfma_f32_16x16x32_bf16 v[32:35], v[168:171], v[194:197], v[32:35]
	v_mfma_f32_16x16x32_bf16 v[24:27], v[160:163], v[202:205], v[24:27]
	v_mfma_f32_16x16x32_bf16 v[16:19], v[168:171], v[202:205], v[16:19]
	v_mfma_f32_16x16x32_bf16 v[8:11], v[160:163], v[210:213], v[8:11]
	v_mfma_f32_16x16x32_bf16 v[0:3], v[168:171], v[210:213], v[0:3]
	v_mfma_f32_16x16x32_bf16 v[56:59], v[164:167], v[180:183], v[56:59]
	v_mfma_f32_16x16x32_bf16 v[48:51], v[172:175], v[180:183], v[48:51]
	v_mfma_f32_16x16x32_bf16 v[40:43], v[164:167], v[198:201], v[40:43]
	v_mfma_f32_16x16x32_bf16 v[32:35], v[172:175], v[198:201], v[32:35]
	v_mfma_f32_16x16x32_bf16 v[24:27], v[164:167], v[206:209], v[24:27]
	v_mfma_f32_16x16x32_bf16 v[16:19], v[172:175], v[206:209], v[16:19]
	v_mfma_f32_16x16x32_bf16 v[8:11], v[164:167], v[228:231], v[8:11]
	v_mfma_f32_16x16x32_bf16 v[0:3], v[172:175], v[228:231], v[0:3]
	s_setprio 0
	s_barrier
	s_add_i32 s51, s51, 2
	s_add_u32 s0, s0, 0x100
	s_addc_u32 s1, s1, 0
	s_add_u32 s49, s49, 0x100
	s_addc_u32 s50, s50, 0
	s_cmp_gt_u32 s51, 13
	s_cbranch_scc0 .LBB0_35
	s_and_b64 vcc, exec, s[12:13]
	s_cbranch_vccz .LBB0_38
	s_barrier
; #define PG8_LAS __attribute__((address_space(3)))
; __device__ __forceinline__ u32x4 pack8(const f32x4 a, const f32x4 b) { u32x4 w; w.x = cvt_pk_bf16(a[0], a[1]); w.y = cvt_pk_bf16(a[2], a[3]); w.z = cvt_pk_bf16(b[0], b[1]); w.w = cvt_pk_bf16(b[2], b[3]); return w; }
;     __device__ __forceinline__ void operator()(const f32x4 (&acc)[2][2][4][2], const Unit& u, int wr, int wc, int fr, int fq) const {
;         PG8_LAS const float* R = stage_rstd((const float*)(ws + WS_PS), lds, u.pm);
; #pragma unroll
;         for (int ai = 0; ai < 2; ++ai)
; #pragma unroll
;             for (int m = 0; m < 4; ++m) {
;                 const int row = u.pm * BM + ai * HALF + wr * 64 + m * 16 + fr;
;                 const float rs = R[ai * HALF + wr * 64 + m * 16 + fr];
;                 bf16_t* ACT = (bf16_t*)(ws + WS_ACT);
;                 f32x4 a[2];
; #pragma unroll
;                 for (int n = 0; n < 2; ++n) {
;                     const f32x4 g = acc[ai][0][m][n] * rs, uu = acc[ai][1][m][n] * rs;
; #pragma unroll
;                     for (int j = 0; j < 4; ++j) a[n][j] = g[j] * __builtin_amdgcn_rcpf(1.0f + __builtin_amdgcn_exp2f(-1.4426950408889634f * g[j])) * uu[j];
;                 }
;                 *(u32x4*)(ACT + (size_t)row * 2816 + u.pn * 128 + wc * 32 + 8 * fq) = pack8(a[0], a[1]);
;             }
;     }
.LBB0_38:
	s_lshl_b32 s3, s48, 8
	ds_read_b32 v146, v142
	v_mov_b32_e32 v148, v120
	v_mov_b32_e32 v149, v124
	v_mov_b32_e32 v124, v121
	s_lshl_b32 s0, s47, 7
	s_waitcnt lgkmcnt(0)
	v_pk_mul_f32 v[148:149], v[148:149], v[146:147] op_sel_hi:[1,0]
	v_add_u32_e32 v144, s3, v140
	v_mul_f32_e32 v120, 0xbfb8aa3b, v149
	v_exp_f32_e32 v120, v120
	s_ashr_i32 s1, s0, 31
	s_movk_i32 s3, 0x1600
	s_lshl_b64 s[0:1], s[0:1], 1
	v_add_f32_e32 v120, 1.0, v120
	v_rcp_f32_e32 v120, v120
	s_andn2_b64 vcc, exec, s[36:37]
	v_mul_f32_e32 v120, v149, v120
	v_mul_f32_e32 v145, v148, v120
	v_pk_mul_f32 v[120:121], v[124:125], v[146:147] op_sel_hi:[1,0]
	s_nop 0
	v_mul_f32_e32 v124, 0xbfb8aa3b, v121
	v_exp_f32_e32 v124, v124
	s_nop 0
	v_add_f32_e32 v124, 1.0, v124
	v_rcp_f32_e32 v124, v124
	s_nop 0
	v_mul_f32_e32 v121, v121, v124
	v_mul_f32_e32 v124, v120, v121
	v_mov_b32_e32 v120, v122
	v_mov_b32_e32 v121, v126
	v_pk_mul_f32 v[120:121], v[120:121], v[146:147] op_sel_hi:[1,0]
	v_mov_b32_e32 v126, v123
	v_mul_f32_e32 v122, 0xbfb8aa3b, v121
	v_exp_f32_e32 v122, v122
	s_nop 0
	v_add_f32_e32 v122, 1.0, v122
	v_rcp_f32_e32 v122, v122
	s_nop 0
	v_mul_f32_e32 v121, v121, v122
	v_mul_f32_e32 v122, v120, v121
	v_pk_mul_f32 v[120:121], v[126:127], v[146:147] op_sel_hi:[1,0]
	s_nop 0
	v_mul_f32_e32 v123, 0xbfb8aa3b, v121
	v_exp_f32_e32 v123, v123
	s_nop 0
	v_add_f32_e32 v123, 1.0, v123
	v_rcp_f32_e32 v123, v123
	s_nop 0
	v_mul_f32_e32 v121, v121, v123
	v_mul_f32_e32 v123, v120, v121
	v_mov_b32_e32 v120, v112
	v_mov_b32_e32 v121, v116
	v_pk_mul_f32 v[120:121], v[120:121], v[146:147] op_sel_hi:[1,0]
	v_mov_b32_e32 v116, v113
	v_mul_f32_e32 v112, 0xbfb8aa3b, v121
	v_exp_f32_e32 v112, v112
	s_nop 0
	v_add_f32_e32 v112, 1.0, v112
	v_rcp_f32_e32 v112, v112
	s_nop 0
	v_mul_f32_e32 v112, v121, v112
	v_mul_f32_e32 v120, v120, v112
	v_pk_mul_f32 v[112:113], v[116:117], v[146:147] op_sel_hi:[1,0]
	s_nop 0
	v_mul_f32_e32 v116, 0xbfb8aa3b, v113
	v_exp_f32_e32 v116, v116
	s_nop 0
	v_add_f32_e32 v116, 1.0, v116
	v_rcp_f32_e32 v116, v116
	s_nop 0
	v_mul_f32_e32 v113, v113, v116
	v_mul_f32_e32 v116, v112, v113
	v_mov_b32_e32 v112, v114
	v_mov_b32_e32 v113, v118
	v_pk_mul_f32 v[112:113], v[112:113], v[146:147] op_sel_hi:[1,0]
	v_mov_b32_e32 v118, v115
	v_mul_f32_e32 v114, 0xbfb8aa3b, v113
	v_exp_f32_e32 v114, v114
	s_nop 0
	v_add_f32_e32 v114, 1.0, v114
	v_rcp_f32_e32 v114, v114
	s_nop 0
	v_mul_f32_e32 v113, v113, v114
	v_mul_f32_e32 v117, v112, v113
	v_pk_mul_f32 v[112:113], v[118:119], v[146:147] op_sel_hi:[1,0]
	s_nop 0
	v_mul_f32_e32 v114, 0xbfb8aa3b, v113
	v_exp_f32_e32 v114, v114
	s_nop 0
	v_add_f32_e32 v114, 1.0, v114
	v_rcp_f32_e32 v114, v114
	s_nop 0
	v_mul_f32_e32 v113, v113, v114
	v_mul_f32_e32 v112, v112, v113
	v_cvt_pk_bf16_f32 v114, v145, v124
	v_cvt_pk_bf16_f32 v115, v122, v123
	v_cvt_pk_bf16_f32 v116, v120, v116
	v_cvt_pk_bf16_f32 v117, v117, v112
	v_mov_b64_e32 v[112:113], s[16:17]
	v_mad_i64_i32 v[118:119], s[4:5], v144, s3, v[112:113]
	v_lshl_add_u64 v[118:119], v[118:119], 0, s[0:1]
	v_lshl_add_u64 v[118:119], v[118:119], 0, s[34:35]
	v_lshl_add_u64 v[118:119], v[118:119], 0, v[184:185]
	global_store_dwordx4 v[118:119], v[114:117], off
	ds_read_b32 v114, v142 offset:64
	s_nop 0
	v_mov_b32_e32 v116, v104
	v_mov_b32_e32 v117, v108
	v_mov_b32_e32 v108, v105
	s_waitcnt lgkmcnt(0)
	v_pk_mul_f32 v[116:117], v[116:117], v[114:115] op_sel_hi:[1,0]
	s_nop 0
	v_mul_f32_e32 v104, 0xbfb8aa3b, v117
	v_exp_f32_e32 v104, v104
	s_nop 0
	v_add_f32_e32 v104, 1.0, v104
	v_rcp_f32_e32 v104, v104
	s_nop 0
	v_mul_f32_e32 v104, v117, v104
	v_mul_f32_e32 v115, v116, v104
	v_pk_mul_f32 v[104:105], v[108:109], v[114:115] op_sel_hi:[1,0]
	s_nop 0
	v_mul_f32_e32 v108, 0xbfb8aa3b, v105
	v_exp_f32_e32 v108, v108
	s_nop 0
	v_add_f32_e32 v108, 1.0, v108
	v_rcp_f32_e32 v108, v108
	s_nop 0
	v_mul_f32_e32 v105, v105, v108
	v_mul_f32_e32 v108, v104, v105
	v_mov_b32_e32 v104, v106
	v_mov_b32_e32 v105, v110
	v_pk_mul_f32 v[104:105], v[104:105], v[114:115] op_sel_hi:[1,0]
	v_mov_b32_e32 v110, v107
	v_mul_f32_e32 v106, 0xbfb8aa3b, v105
	v_exp_f32_e32 v106, v106
	s_nop 0
	v_add_f32_e32 v106, 1.0, v106
	v_rcp_f32_e32 v106, v106
	s_nop 0
	v_mul_f32_e32 v105, v105, v106
	v_mul_f32_e32 v106, v104, v105
	v_pk_mul_f32 v[104:105], v[110:111], v[114:115] op_sel_hi:[1,0]
	s_nop 0
	v_mul_f32_e32 v107, 0xbfb8aa3b, v105
	v_exp_f32_e32 v107, v107
	s_nop 0
	v_add_f32_e32 v107, 1.0, v107
	v_rcp_f32_e32 v107, v107
	s_nop 0
	v_mul_f32_e32 v105, v105, v107
	v_mul_f32_e32 v107, v104, v105
	v_mov_b32_e32 v104, v96
	v_mov_b32_e32 v105, v100
	v_pk_mul_f32 v[104:105], v[104:105], v[114:115] op_sel_hi:[1,0]
	v_mov_b32_e32 v100, v97
	v_mul_f32_e32 v96, 0xbfb8aa3b, v105
	v_exp_f32_e32 v96, v96
	s_nop 0
	v_add_f32_e32 v96, 1.0, v96
	v_rcp_f32_e32 v96, v96
	s_nop 0
	v_mul_f32_e32 v96, v105, v96
	v_mul_f32_e32 v104, v104, v96
	v_pk_mul_f32 v[96:97], v[100:101], v[114:115] op_sel_hi:[1,0]
	s_nop 0
	v_mul_f32_e32 v100, 0xbfb8aa3b, v97
	v_exp_f32_e32 v100, v100
	s_nop 0
	v_add_f32_e32 v100, 1.0, v100
	v_rcp_f32_e32 v100, v100
	s_nop 0
	v_mul_f32_e32 v97, v97, v100
	v_mul_f32_e32 v100, v96, v97
	v_mov_b32_e32 v96, v98
	v_mov_b32_e32 v97, v102
	v_pk_mul_f32 v[96:97], v[96:97], v[114:115] op_sel_hi:[1,0]
	v_mov_b32_e32 v102, v99
	v_mul_f32_e32 v98, 0xbfb8aa3b, v97
	v_exp_f32_e32 v98, v98
	s_nop 0
	v_add_f32_e32 v98, 1.0, v98
	v_rcp_f32_e32 v98, v98
	s_nop 0
	v_mul_f32_e32 v97, v97, v98
	v_mul_f32_e32 v101, v96, v97
	v_pk_mul_f32 v[96:97], v[102:103], v[114:115] op_sel_hi:[1,0]
	v_or_b32_e32 v102, 16, v144
	v_mul_f32_e32 v98, 0xbfb8aa3b, v97
	v_exp_f32_e32 v98, v98
	s_nop 0
	v_add_f32_e32 v98, 1.0, v98
	v_rcp_f32_e32 v98, v98
	s_nop 0
	v_mul_f32_e32 v97, v97, v98
	v_mul_f32_e32 v99, v96, v97
	v_cvt_pk_bf16_f32 v96, v115, v108
	v_cvt_pk_bf16_f32 v97, v106, v107
	v_cvt_pk_bf16_f32 v98, v104, v100
	v_cvt_pk_bf16_f32 v99, v101, v99
	v_mad_i64_i32 v[100:101], s[4:5], v102, s3, v[112:113]
	v_lshl_add_u64 v[100:101], v[100:101], 0, s[0:1]
	v_lshl_add_u64 v[100:101], v[100:101], 0, s[34:35]
	v_lshl_add_u64 v[100:101], v[100:101], 0, v[184:185]
	global_store_dwordx4 v[100:101], v[96:99], off
	ds_read_b32 v96, v142 offset:128
	s_nop 0
	v_mov_b32_e32 v98, v88
	v_mov_b32_e32 v99, v92
	v_mov_b32_e32 v92, v89
	s_waitcnt lgkmcnt(0)
; __device__ __forceinline__ u32x4 pack8(const f32x4 a, const f32x4 b) { u32x4 w; w.x = cvt_pk_bf16(a[0], a[1]); w.y = cvt_pk_bf16(a[2], a[3]); w.z = cvt_pk_bf16(b[0], b[1]); w.w = cvt_pk_bf16(b[2], b[3]); return w; }
;     __device__ __forceinline__ void operator()(const f32x4 (&acc)[2][2][4][2], const Unit& u, int wr, int wc, int fr, int fq) const {
;     ...
;         for (int ai = 0; ai < 2; ++ai)
; #pragma unroll
;             for (int m = 0; m < 4; ++m) {
;                 const int row = u.pm * BM + ai * HALF + wr * 64 + m * 16 + fr;
;                 const float rs = R[ai * HALF + wr * 64 + m * 16 + fr];
;                 bf16_t* ACT = (bf16_t*)(ws + WS_ACT);
;                 f32x4 a[2];
; #pragma unroll
;                 for (int n = 0; n < 2; ++n) {
;                     const f32x4 g = acc[ai][0][m][n] * rs, uu = acc[ai][1][m][n] * rs;
; #pragma unroll
;                     for (int j = 0; j < 4; ++j) a[n][j] = g[j] * __builtin_amdgcn_rcpf(1.0f + __builtin_amdgcn_exp2f(-1.4426950408889634f * g[j])) * uu[j];
;                 }
;                 *(u32x4*)(ACT + (size_t)row * 2816 + u.pn * 128 + wc * 32 + 8 * fq) = pack8(a[0], a[1]);
;             }
;     }
	v_pk_mul_f32 v[98:99], v[98:99], v[96:97] op_sel_hi:[1,0]
	s_nop 0
	v_mul_f32_e32 v88, 0xbfb8aa3b, v99
	v_exp_f32_e32 v88, v88
	s_nop 0
	v_add_f32_e32 v88, 1.0, v88
	v_rcp_f32_e32 v88, v88
	s_nop 0
	v_mul_f32_e32 v88, v99, v88
	v_mul_f32_e32 v97, v98, v88
	v_pk_mul_f32 v[88:89], v[92:93], v[96:97] op_sel_hi:[1,0]
	s_nop 0
	v_mul_f32_e32 v92, 0xbfb8aa3b, v89
	v_exp_f32_e32 v92, v92
	s_nop 0
	v_add_f32_e32 v92, 1.0, v92
	v_rcp_f32_e32 v92, v92
	s_nop 0
	v_mul_f32_e32 v89, v89, v92
	v_mul_f32_e32 v92, v88, v89
	v_mov_b32_e32 v88, v90
	v_mov_b32_e32 v89, v94
	v_pk_mul_f32 v[88:89], v[88:89], v[96:97] op_sel_hi:[1,0]
	v_mov_b32_e32 v94, v91
	v_mul_f32_e32 v90, 0xbfb8aa3b, v89
	v_exp_f32_e32 v90, v90
	s_nop 0
	v_add_f32_e32 v90, 1.0, v90
	v_rcp_f32_e32 v90, v90
	s_nop 0
	v_mul_f32_e32 v89, v89, v90
	v_mul_f32_e32 v90, v88, v89
	v_pk_mul_f32 v[88:89], v[94:95], v[96:97] op_sel_hi:[1,0]
	s_nop 0
	v_mul_f32_e32 v91, 0xbfb8aa3b, v89
	v_exp_f32_e32 v91, v91
	s_nop 0
	v_add_f32_e32 v91, 1.0, v91
	v_rcp_f32_e32 v91, v91
	s_nop 0
	v_mul_f32_e32 v89, v89, v91
	v_mul_f32_e32 v91, v88, v89
	v_mov_b32_e32 v88, v80
	v_mov_b32_e32 v89, v84
	v_pk_mul_f32 v[88:89], v[88:89], v[96:97] op_sel_hi:[1,0]
	v_mov_b32_e32 v84, v81
	v_mul_f32_e32 v80, 0xbfb8aa3b, v89
	v_exp_f32_e32 v80, v80
	s_nop 0
	v_add_f32_e32 v80, 1.0, v80
	v_rcp_f32_e32 v80, v80
	s_nop 0
	v_mul_f32_e32 v80, v89, v80
	v_mul_f32_e32 v88, v88, v80
	v_pk_mul_f32 v[80:81], v[84:85], v[96:97] op_sel_hi:[1,0]
	s_nop 0
	v_mul_f32_e32 v84, 0xbfb8aa3b, v81
	v_exp_f32_e32 v84, v84
	s_nop 0
	v_add_f32_e32 v84, 1.0, v84
	v_rcp_f32_e32 v84, v84
	s_nop 0
	v_mul_f32_e32 v81, v81, v84
	v_mul_f32_e32 v84, v80, v81
	v_mov_b32_e32 v80, v82
	v_mov_b32_e32 v81, v86
	v_pk_mul_f32 v[80:81], v[80:81], v[96:97] op_sel_hi:[1,0]
	v_mov_b32_e32 v86, v83
	v_mul_f32_e32 v82, 0xbfb8aa3b, v81
	v_exp_f32_e32 v82, v82
	s_nop 0
	v_add_f32_e32 v82, 1.0, v82
	v_rcp_f32_e32 v82, v82
	s_nop 0
	v_mul_f32_e32 v81, v81, v82
	v_mul_f32_e32 v85, v80, v81
	v_pk_mul_f32 v[80:81], v[86:87], v[96:97] op_sel_hi:[1,0]
	v_or_b32_e32 v86, 32, v144
	v_mul_f32_e32 v82, 0xbfb8aa3b, v81
	v_exp_f32_e32 v82, v82
	s_nop 0
	v_add_f32_e32 v82, 1.0, v82
	v_rcp_f32_e32 v82, v82
	s_nop 0
	v_mul_f32_e32 v81, v81, v82
	v_mul_f32_e32 v83, v80, v81
	v_cvt_pk_bf16_f32 v80, v97, v92
	v_cvt_pk_bf16_f32 v81, v90, v91
	v_cvt_pk_bf16_f32 v82, v88, v84
	v_cvt_pk_bf16_f32 v83, v85, v83
	v_mad_i64_i32 v[84:85], s[4:5], v86, s3, v[112:113]
	v_lshl_add_u64 v[84:85], v[84:85], 0, s[0:1]
	v_lshl_add_u64 v[84:85], v[84:85], 0, s[34:35]
	v_lshl_add_u64 v[84:85], v[84:85], 0, v[184:185]
	global_store_dwordx4 v[84:85], v[80:83], off
	ds_read_b32 v80, v142 offset:192
	s_nop 0
	v_mov_b32_e32 v82, v72
	v_mov_b32_e32 v83, v76
	v_mov_b32_e32 v76, v73
	s_waitcnt lgkmcnt(0)
	v_pk_mul_f32 v[82:83], v[82:83], v[80:81] op_sel_hi:[1,0]
	s_nop 0
	v_mul_f32_e32 v72, 0xbfb8aa3b, v83
	v_exp_f32_e32 v72, v72
	s_nop 0
	v_add_f32_e32 v72, 1.0, v72
	v_rcp_f32_e32 v72, v72
	s_nop 0
	v_mul_f32_e32 v72, v83, v72
	v_mul_f32_e32 v81, v82, v72
	v_pk_mul_f32 v[72:73], v[76:77], v[80:81] op_sel_hi:[1,0]
	s_nop 0
	v_mul_f32_e32 v76, 0xbfb8aa3b, v73
	v_exp_f32_e32 v76, v76
	s_nop 0
	v_add_f32_e32 v76, 1.0, v76
	v_rcp_f32_e32 v76, v76
	s_nop 0
	v_mul_f32_e32 v73, v73, v76
	v_mul_f32_e32 v76, v72, v73
	v_mov_b32_e32 v72, v74
	v_mov_b32_e32 v73, v78
	v_pk_mul_f32 v[72:73], v[72:73], v[80:81] op_sel_hi:[1,0]
	v_mov_b32_e32 v78, v75
	v_mul_f32_e32 v74, 0xbfb8aa3b, v73
	v_exp_f32_e32 v74, v74
	s_nop 0
	v_add_f32_e32 v74, 1.0, v74
	v_rcp_f32_e32 v74, v74
	s_nop 0
	v_mul_f32_e32 v73, v73, v74
	v_mul_f32_e32 v74, v72, v73
	v_pk_mul_f32 v[72:73], v[78:79], v[80:81] op_sel_hi:[1,0]
	s_nop 0
	v_mul_f32_e32 v75, 0xbfb8aa3b, v73
	v_exp_f32_e32 v75, v75
	s_nop 0
	v_add_f32_e32 v75, 1.0, v75
	v_rcp_f32_e32 v75, v75
	s_nop 0
	v_mul_f32_e32 v73, v73, v75
	v_mul_f32_e32 v75, v72, v73
	v_mov_b32_e32 v72, v64
	v_mov_b32_e32 v73, v68
	v_pk_mul_f32 v[72:73], v[72:73], v[80:81] op_sel_hi:[1,0]
	v_mov_b32_e32 v68, v65
	v_mul_f32_e32 v64, 0xbfb8aa3b, v73
	v_exp_f32_e32 v64, v64
	s_nop 0
	v_add_f32_e32 v64, 1.0, v64
	v_rcp_f32_e32 v64, v64
	s_nop 0
	v_mul_f32_e32 v64, v73, v64
	v_mul_f32_e32 v72, v72, v64
	v_pk_mul_f32 v[64:65], v[68:69], v[80:81] op_sel_hi:[1,0]
	s_nop 0
	v_mul_f32_e32 v68, 0xbfb8aa3b, v65
	v_exp_f32_e32 v68, v68
	s_nop 0
	v_add_f32_e32 v68, 1.0, v68
	v_rcp_f32_e32 v68, v68
	s_nop 0
	v_mul_f32_e32 v65, v65, v68
	v_mul_f32_e32 v68, v64, v65
	v_mov_b32_e32 v64, v66
	v_mov_b32_e32 v65, v70
	v_pk_mul_f32 v[64:65], v[64:65], v[80:81] op_sel_hi:[1,0]
	v_mov_b32_e32 v70, v67
	v_mul_f32_e32 v66, 0xbfb8aa3b, v65
	v_exp_f32_e32 v66, v66
	s_nop 0
	v_add_f32_e32 v66, 1.0, v66
	v_rcp_f32_e32 v66, v66
	s_nop 0
	v_mul_f32_e32 v65, v65, v66
	v_mul_f32_e32 v69, v64, v65
	v_pk_mul_f32 v[64:65], v[70:71], v[80:81] op_sel_hi:[1,0]
	v_or_b32_e32 v70, 48, v144
	v_mul_f32_e32 v66, 0xbfb8aa3b, v65
	v_exp_f32_e32 v66, v66
	s_nop 0
	v_add_f32_e32 v66, 1.0, v66
	v_rcp_f32_e32 v66, v66
	s_nop 0
	v_mul_f32_e32 v65, v65, v66
	v_mul_f32_e32 v67, v64, v65
	v_cvt_pk_bf16_f32 v64, v81, v76
	v_cvt_pk_bf16_f32 v65, v74, v75
	v_cvt_pk_bf16_f32 v66, v72, v68
	v_cvt_pk_bf16_f32 v67, v69, v67
	v_mad_i64_i32 v[68:69], s[4:5], v70, s3, v[112:113]
	v_lshl_add_u64 v[68:69], v[68:69], 0, s[0:1]
	v_lshl_add_u64 v[68:69], v[68:69], 0, s[34:35]
	v_lshl_add_u64 v[68:69], v[68:69], 0, v[184:185]
	global_store_dwordx4 v[68:69], v[64:67], off
	ds_read_b32 v64, v142 offset:512
	s_nop 0
	v_add_u32_e32 v65, 0x80, v144
	v_mov_b32_e32 v66, v56
	v_mov_b32_e32 v67, v60
	s_waitcnt lgkmcnt(0)
; __device__ __forceinline__ u32x4 pack8(const f32x4 a, const f32x4 b) { u32x4 w; w.x = cvt_pk_bf16(a[0], a[1]); w.y = cvt_pk_bf16(a[2], a[3]); w.z = cvt_pk_bf16(b[0], b[1]); w.w = cvt_pk_bf16(b[2], b[3]); return w; }
;     __device__ __forceinline__ void operator()(const f32x4 (&acc)[2][2][4][2], const Unit& u, int wr, int wc, int fr, int fq) const {
;     ...
;         for (int ai = 0; ai < 2; ++ai)
; #pragma unroll
;             for (int m = 0; m < 4; ++m) {
;                 const int row = u.pm * BM + ai * HALF + wr * 64 + m * 16 + fr;
;                 const float rs = R[ai * HALF + wr * 64 + m * 16 + fr];
;                 bf16_t* ACT = (bf16_t*)(ws + WS_ACT);
;                 f32x4 a[2];
; #pragma unroll
;                 for (int n = 0; n < 2; ++n) {
;                     const f32x4 g = acc[ai][0][m][n] * rs, uu = acc[ai][1][m][n] * rs;
; #pragma unroll
;                     for (int j = 0; j < 4; ++j) a[n][j] = g[j] * __builtin_amdgcn_rcpf(1.0f + __builtin_amdgcn_exp2f(-1.4426950408889634f * g[j])) * uu[j];
;                 }
;                 *(u32x4*)(ACT + (size_t)row * 2816 + u.pn * 128 + wc * 32 + 8 * fq) = pack8(a[0], a[1]);
;             }
;     }
	v_pk_mul_f32 v[66:67], v[66:67], v[64:65] op_sel_hi:[1,0]
	v_mov_b32_e32 v60, v57
	v_mul_f32_e32 v56, 0xbfb8aa3b, v67
	v_exp_f32_e32 v56, v56
	s_nop 0
	v_add_f32_e32 v56, 1.0, v56
	v_rcp_f32_e32 v56, v56
	s_nop 0
	v_mul_f32_e32 v56, v67, v56
	v_mul_f32_e32 v66, v66, v56
	v_pk_mul_f32 v[56:57], v[60:61], v[64:65] op_sel_hi:[1,0]
	s_nop 0
	v_mul_f32_e32 v60, 0xbfb8aa3b, v57
	v_exp_f32_e32 v60, v60
	s_nop 0
	v_add_f32_e32 v60, 1.0, v60
	v_rcp_f32_e32 v60, v60
	s_nop 0
	v_mul_f32_e32 v57, v57, v60
	v_mul_f32_e32 v60, v56, v57
	v_mov_b32_e32 v56, v58
	v_mov_b32_e32 v57, v62
	v_pk_mul_f32 v[56:57], v[56:57], v[64:65] op_sel_hi:[1,0]
	v_mov_b32_e32 v62, v59
	v_mul_f32_e32 v58, 0xbfb8aa3b, v57
	v_exp_f32_e32 v58, v58
	s_nop 0
	v_add_f32_e32 v58, 1.0, v58
	v_rcp_f32_e32 v58, v58
	s_nop 0
	v_mul_f32_e32 v57, v57, v58
	v_mul_f32_e32 v58, v56, v57
	v_pk_mul_f32 v[56:57], v[62:63], v[64:65] op_sel_hi:[1,0]
	s_nop 0
	v_mul_f32_e32 v59, 0xbfb8aa3b, v57
	v_exp_f32_e32 v59, v59
	s_nop 0
	v_add_f32_e32 v59, 1.0, v59
	v_rcp_f32_e32 v59, v59
	s_nop 0
	v_mul_f32_e32 v57, v57, v59
	v_mul_f32_e32 v59, v56, v57
	v_mov_b32_e32 v56, v48
	v_mov_b32_e32 v57, v52
	v_pk_mul_f32 v[56:57], v[56:57], v[64:65] op_sel_hi:[1,0]
	v_mov_b32_e32 v52, v49
	v_mul_f32_e32 v48, 0xbfb8aa3b, v57
	v_exp_f32_e32 v48, v48
	s_nop 0
	v_add_f32_e32 v48, 1.0, v48
	v_rcp_f32_e32 v48, v48
	s_nop 0
	v_mul_f32_e32 v48, v57, v48
	v_mul_f32_e32 v56, v56, v48
	v_pk_mul_f32 v[48:49], v[52:53], v[64:65] op_sel_hi:[1,0]
	s_nop 0
	v_mul_f32_e32 v52, 0xbfb8aa3b, v49
	v_exp_f32_e32 v52, v52
	s_nop 0
	v_add_f32_e32 v52, 1.0, v52
	v_rcp_f32_e32 v52, v52
	s_nop 0
	v_mul_f32_e32 v49, v49, v52
	v_mul_f32_e32 v52, v48, v49
	v_mov_b32_e32 v48, v50
	v_mov_b32_e32 v49, v54
	v_pk_mul_f32 v[48:49], v[48:49], v[64:65] op_sel_hi:[1,0]
	v_mov_b32_e32 v54, v51
	v_mul_f32_e32 v50, 0xbfb8aa3b, v49
	v_exp_f32_e32 v50, v50
	s_nop 0
	v_add_f32_e32 v50, 1.0, v50
	v_rcp_f32_e32 v50, v50
	s_nop 0
	v_mul_f32_e32 v49, v49, v50
	v_mul_f32_e32 v53, v48, v49
	v_pk_mul_f32 v[48:49], v[54:55], v[64:65] op_sel_hi:[1,0]
	s_nop 0
	v_mul_f32_e32 v50, 0xbfb8aa3b, v49
	v_exp_f32_e32 v50, v50
	s_nop 0
	v_add_f32_e32 v50, 1.0, v50
	v_rcp_f32_e32 v50, v50
	s_nop 0
	v_mul_f32_e32 v49, v49, v50
	v_mul_f32_e32 v51, v48, v49
	v_cvt_pk_bf16_f32 v48, v66, v60
	v_cvt_pk_bf16_f32 v49, v58, v59
	v_cvt_pk_bf16_f32 v50, v56, v52
	v_cvt_pk_bf16_f32 v51, v53, v51
	v_mad_i64_i32 v[52:53], s[4:5], v65, s3, v[112:113]
	v_lshl_add_u64 v[52:53], v[52:53], 0, s[0:1]
	v_lshl_add_u64 v[52:53], v[52:53], 0, s[34:35]
	v_lshl_add_u64 v[52:53], v[52:53], 0, v[184:185]
	global_store_dwordx4 v[52:53], v[48:51], off
	ds_read_b32 v48, v142 offset:576
	s_nop 0
	v_mov_b32_e32 v50, v40
	v_mov_b32_e32 v51, v44
	v_mov_b32_e32 v44, v41
	s_waitcnt lgkmcnt(0)
	v_pk_mul_f32 v[50:51], v[50:51], v[48:49] op_sel_hi:[1,0]
	s_nop 0
	v_mul_f32_e32 v40, 0xbfb8aa3b, v51
	v_exp_f32_e32 v40, v40
	s_nop 0
	v_add_f32_e32 v40, 1.0, v40
	v_rcp_f32_e32 v40, v40
	s_nop 0
	v_mul_f32_e32 v40, v51, v40
	v_mul_f32_e32 v49, v50, v40
	v_pk_mul_f32 v[40:41], v[44:45], v[48:49] op_sel_hi:[1,0]
	s_nop 0
	v_mul_f32_e32 v44, 0xbfb8aa3b, v41
	v_exp_f32_e32 v44, v44
	s_nop 0
	v_add_f32_e32 v44, 1.0, v44
	v_rcp_f32_e32 v44, v44
	s_nop 0
	v_mul_f32_e32 v41, v41, v44
	v_mul_f32_e32 v44, v40, v41
	v_mov_b32_e32 v40, v42
	v_mov_b32_e32 v41, v46
	v_pk_mul_f32 v[40:41], v[40:41], v[48:49] op_sel_hi:[1,0]
	v_mov_b32_e32 v46, v43
	v_mul_f32_e32 v42, 0xbfb8aa3b, v41
	v_exp_f32_e32 v42, v42
	s_nop 0
	v_add_f32_e32 v42, 1.0, v42
	v_rcp_f32_e32 v42, v42
	s_nop 0
	v_mul_f32_e32 v41, v41, v42
	v_mul_f32_e32 v42, v40, v41
	v_pk_mul_f32 v[40:41], v[46:47], v[48:49] op_sel_hi:[1,0]
	s_nop 0
	v_mul_f32_e32 v43, 0xbfb8aa3b, v41
	v_exp_f32_e32 v43, v43
	s_nop 0
	v_add_f32_e32 v43, 1.0, v43
	v_rcp_f32_e32 v43, v43
	s_nop 0
	v_mul_f32_e32 v41, v41, v43
	v_mul_f32_e32 v43, v40, v41
	v_mov_b32_e32 v40, v32
	v_mov_b32_e32 v41, v36
	v_pk_mul_f32 v[40:41], v[40:41], v[48:49] op_sel_hi:[1,0]
	v_mov_b32_e32 v36, v33
	v_mul_f32_e32 v32, 0xbfb8aa3b, v41
	v_exp_f32_e32 v32, v32
	s_nop 0
	v_add_f32_e32 v32, 1.0, v32
	v_rcp_f32_e32 v32, v32
	s_nop 0
	v_mul_f32_e32 v32, v41, v32
	v_mul_f32_e32 v40, v40, v32
	v_pk_mul_f32 v[32:33], v[36:37], v[48:49] op_sel_hi:[1,0]
	s_nop 0
	v_mul_f32_e32 v36, 0xbfb8aa3b, v33
	v_exp_f32_e32 v36, v36
	s_nop 0
	v_add_f32_e32 v36, 1.0, v36
	v_rcp_f32_e32 v36, v36
	s_nop 0
	v_mul_f32_e32 v33, v33, v36
	v_mul_f32_e32 v36, v32, v33
	v_mov_b32_e32 v32, v34
	v_mov_b32_e32 v33, v38
	v_pk_mul_f32 v[32:33], v[32:33], v[48:49] op_sel_hi:[1,0]
	v_mov_b32_e32 v38, v35
	v_mul_f32_e32 v34, 0xbfb8aa3b, v33
	v_exp_f32_e32 v34, v34
	s_nop 0
	v_add_f32_e32 v34, 1.0, v34
	v_rcp_f32_e32 v34, v34
	s_nop 0
	v_mul_f32_e32 v33, v33, v34
	v_mul_f32_e32 v37, v32, v33
	v_pk_mul_f32 v[32:33], v[38:39], v[48:49] op_sel_hi:[1,0]
	v_add_u32_e32 v38, 0x90, v144
	v_mul_f32_e32 v34, 0xbfb8aa3b, v33
	v_exp_f32_e32 v34, v34
	s_nop 0
	v_add_f32_e32 v34, 1.0, v34
	v_rcp_f32_e32 v34, v34
	s_nop 0
	v_mul_f32_e32 v33, v33, v34
	v_mul_f32_e32 v35, v32, v33
	v_cvt_pk_bf16_f32 v32, v49, v44
	v_cvt_pk_bf16_f32 v33, v42, v43
	v_cvt_pk_bf16_f32 v34, v40, v36
	v_cvt_pk_bf16_f32 v35, v37, v35
	v_mad_i64_i32 v[36:37], s[4:5], v38, s3, v[112:113]
	v_lshl_add_u64 v[36:37], v[36:37], 0, s[0:1]
	v_lshl_add_u64 v[36:37], v[36:37], 0, s[34:35]
	v_lshl_add_u64 v[36:37], v[36:37], 0, v[184:185]
	global_store_dwordx4 v[36:37], v[32:35], off
	ds_read_b32 v32, v142 offset:640
	s_nop 0
	v_mov_b32_e32 v34, v24
	v_mov_b32_e32 v35, v28
	v_mov_b32_e32 v28, v25
	s_waitcnt lgkmcnt(0)
; __device__ __forceinline__ u32x4 pack8(const f32x4 a, const f32x4 b) { u32x4 w; w.x = cvt_pk_bf16(a[0], a[1]); w.y = cvt_pk_bf16(a[2], a[3]); w.z = cvt_pk_bf16(b[0], b[1]); w.w = cvt_pk_bf16(b[2], b[3]); return w; }
; #define PG8_BAR __builtin_amdgcn_s_barrier()
;     __device__ __forceinline__ void operator()(const f32x4 (&acc)[2][2][4][2], const Unit& u, int wr, int wc, int fr, int fq) const {
;     ...
;         for (int ai = 0; ai < 2; ++ai)
; #pragma unroll
;             for (int m = 0; m < 4; ++m) {
;                 const int row = u.pm * BM + ai * HALF + wr * 64 + m * 16 + fr;
;                 const float rs = R[ai * HALF + wr * 64 + m * 16 + fr];
;                 bf16_t* ACT = (bf16_t*)(ws + WS_ACT);
;                 f32x4 a[2];
; #pragma unroll
;                 for (int n = 0; n < 2; ++n) {
;                     const f32x4 g = acc[ai][0][m][n] * rs, uu = acc[ai][1][m][n] * rs;
; #pragma unroll
;                     for (int j = 0; j < 4; ++j) a[n][j] = g[j] * __builtin_amdgcn_rcpf(1.0f + __builtin_amdgcn_exp2f(-1.4426950408889634f * g[j])) * uu[j];
;                 }
;                 *(u32x4*)(ACT + (size_t)row * 2816 + u.pn * 128 + wc * 32 + 8 * fq) = pack8(a[0], a[1]);
;             }
;     }
; template <class Epi, class Sched, bool ALIGN_EPI = false, bool SP2 = false>
; __device__ __forceinline__ void gemm_phase(PG8_LAS unsigned char* lds, const Gemm g, const Sched& S, const Epi& E) {
;     ...
;         if constexpr (!Epi::AFTER_DRAIN) { E(acc, cur, wr, wc, fr, fq); S.done(cur); }
;         if (!has_next) break;
; #pragma unroll
;         for (int a = 0; a < 2; ++a)
; #pragma unroll
;             for (int b = 0; b < 2; ++b)
; #pragma unroll
;                 for (int m = 0; m < 4; ++m)
; #pragma unroll
;                     for (int n = 0; n < 2; ++n) acc[a][b][m][n] = (f32x4){0.f, 0.f, 0.f, 0.f};
;         cur = nxt; cA = nA; cB = nB; ++ui;
;         if constexpr (ALIGN_EPI) { if (wr == 1) PG8_BAR; }
;     }
	v_pk_mul_f32 v[34:35], v[34:35], v[32:33] op_sel_hi:[1,0]
	s_nop 0
	v_mul_f32_e32 v24, 0xbfb8aa3b, v35
	v_exp_f32_e32 v24, v24
	s_nop 0
	v_add_f32_e32 v24, 1.0, v24
	v_rcp_f32_e32 v24, v24
	s_nop 0
	v_mul_f32_e32 v24, v35, v24
	v_mul_f32_e32 v33, v34, v24
	v_pk_mul_f32 v[24:25], v[28:29], v[32:33] op_sel_hi:[1,0]
	s_nop 0
	v_mul_f32_e32 v28, 0xbfb8aa3b, v25
	v_exp_f32_e32 v28, v28
	s_nop 0
	v_add_f32_e32 v28, 1.0, v28
	v_rcp_f32_e32 v28, v28
	s_nop 0
	v_mul_f32_e32 v25, v25, v28
	v_mul_f32_e32 v28, v24, v25
	v_mov_b32_e32 v24, v26
	v_mov_b32_e32 v25, v30
	v_pk_mul_f32 v[24:25], v[24:25], v[32:33] op_sel_hi:[1,0]
	v_mov_b32_e32 v30, v27
	v_mul_f32_e32 v26, 0xbfb8aa3b, v25
	v_exp_f32_e32 v26, v26
	s_nop 0
	v_add_f32_e32 v26, 1.0, v26
	v_rcp_f32_e32 v26, v26
	s_nop 0
	v_mul_f32_e32 v25, v25, v26
	v_mul_f32_e32 v26, v24, v25
	v_pk_mul_f32 v[24:25], v[30:31], v[32:33] op_sel_hi:[1,0]
	s_nop 0
	v_mul_f32_e32 v27, 0xbfb8aa3b, v25
	v_exp_f32_e32 v27, v27
	s_nop 0
	v_add_f32_e32 v27, 1.0, v27
	v_rcp_f32_e32 v27, v27
	s_nop 0
	v_mul_f32_e32 v25, v25, v27
	v_mul_f32_e32 v27, v24, v25
	v_mov_b32_e32 v24, v16
	v_mov_b32_e32 v25, v20
	v_pk_mul_f32 v[24:25], v[24:25], v[32:33] op_sel_hi:[1,0]
	v_mov_b32_e32 v20, v17
	v_mul_f32_e32 v16, 0xbfb8aa3b, v25
	v_exp_f32_e32 v16, v16
	s_nop 0
	v_add_f32_e32 v16, 1.0, v16
	v_rcp_f32_e32 v16, v16
	s_nop 0
	v_mul_f32_e32 v16, v25, v16
	v_mul_f32_e32 v24, v24, v16
	v_pk_mul_f32 v[16:17], v[20:21], v[32:33] op_sel_hi:[1,0]
	s_nop 0
	v_mul_f32_e32 v20, 0xbfb8aa3b, v17
	v_exp_f32_e32 v20, v20
	s_nop 0
	v_add_f32_e32 v20, 1.0, v20
	v_rcp_f32_e32 v20, v20
	s_nop 0
	v_mul_f32_e32 v17, v17, v20
	v_mul_f32_e32 v20, v16, v17
	v_mov_b32_e32 v16, v18
	v_mov_b32_e32 v17, v22
	v_pk_mul_f32 v[16:17], v[16:17], v[32:33] op_sel_hi:[1,0]
	v_mov_b32_e32 v22, v19
	v_mul_f32_e32 v18, 0xbfb8aa3b, v17
	v_exp_f32_e32 v18, v18
	s_nop 0
	v_add_f32_e32 v18, 1.0, v18
	v_rcp_f32_e32 v18, v18
	s_nop 0
	v_mul_f32_e32 v17, v17, v18
	v_mul_f32_e32 v21, v16, v17
	v_pk_mul_f32 v[16:17], v[22:23], v[32:33] op_sel_hi:[1,0]
	v_add_u32_e32 v22, 0xa0, v144
	v_mul_f32_e32 v18, 0xbfb8aa3b, v17
	v_exp_f32_e32 v18, v18
	s_nop 0
	v_add_f32_e32 v18, 1.0, v18
	v_rcp_f32_e32 v18, v18
	s_nop 0
	v_mul_f32_e32 v17, v17, v18
	v_mul_f32_e32 v19, v16, v17
	v_cvt_pk_bf16_f32 v16, v33, v28
	v_cvt_pk_bf16_f32 v17, v26, v27
	v_cvt_pk_bf16_f32 v18, v24, v20
	v_cvt_pk_bf16_f32 v19, v21, v19
	v_mad_i64_i32 v[20:21], s[4:5], v22, s3, v[112:113]
	v_lshl_add_u64 v[20:21], v[20:21], 0, s[0:1]
	v_lshl_add_u64 v[20:21], v[20:21], 0, s[34:35]
	v_lshl_add_u64 v[20:21], v[20:21], 0, v[184:185]
	global_store_dwordx4 v[20:21], v[16:19], off
	ds_read_b32 v16, v142 offset:704
	s_nop 0
	v_mov_b32_e32 v18, v8
	v_mov_b32_e32 v19, v12
	v_mov_b32_e32 v12, v9
	s_waitcnt lgkmcnt(0)
	v_pk_mul_f32 v[18:19], v[18:19], v[16:17] op_sel_hi:[1,0]
	s_nop 0
	v_mul_f32_e32 v8, 0xbfb8aa3b, v19
	v_exp_f32_e32 v8, v8
	s_nop 0
	v_add_f32_e32 v8, 1.0, v8
	v_rcp_f32_e32 v8, v8
	s_nop 0
	v_mul_f32_e32 v8, v19, v8
	v_mul_f32_e32 v17, v18, v8
	v_pk_mul_f32 v[8:9], v[12:13], v[16:17] op_sel_hi:[1,0]
	s_nop 0
	v_mul_f32_e32 v12, 0xbfb8aa3b, v9
	v_exp_f32_e32 v12, v12
	s_nop 0
	v_add_f32_e32 v12, 1.0, v12
	v_rcp_f32_e32 v12, v12
	s_nop 0
	v_mul_f32_e32 v9, v9, v12
	v_mul_f32_e32 v12, v8, v9
	v_mov_b32_e32 v8, v10
	v_mov_b32_e32 v9, v14
	v_pk_mul_f32 v[8:9], v[8:9], v[16:17] op_sel_hi:[1,0]
	v_mov_b32_e32 v14, v11
	v_mul_f32_e32 v10, 0xbfb8aa3b, v9
	v_exp_f32_e32 v10, v10
	s_nop 0
	v_add_f32_e32 v10, 1.0, v10
	v_rcp_f32_e32 v10, v10
	s_nop 0
	v_mul_f32_e32 v9, v9, v10
	v_mul_f32_e32 v10, v8, v9
	v_pk_mul_f32 v[8:9], v[14:15], v[16:17] op_sel_hi:[1,0]
	s_nop 0
	v_mul_f32_e32 v11, 0xbfb8aa3b, v9
	v_exp_f32_e32 v11, v11
	s_nop 0
	v_add_f32_e32 v11, 1.0, v11
	v_rcp_f32_e32 v11, v11
	s_nop 0
	v_mul_f32_e32 v9, v9, v11
	v_mul_f32_e32 v11, v8, v9
	v_mov_b32_e32 v8, v0
	v_mov_b32_e32 v9, v4
	v_pk_mul_f32 v[8:9], v[8:9], v[16:17] op_sel_hi:[1,0]
	v_mov_b32_e32 v4, v1
	v_mul_f32_e32 v0, 0xbfb8aa3b, v9
	v_exp_f32_e32 v0, v0
	s_nop 0
	v_add_f32_e32 v0, 1.0, v0
	v_rcp_f32_e32 v0, v0
	s_nop 0
	v_mul_f32_e32 v0, v9, v0
	v_mul_f32_e32 v8, v8, v0
	v_pk_mul_f32 v[0:1], v[4:5], v[16:17] op_sel_hi:[1,0]
	s_nop 0
	v_mul_f32_e32 v4, 0xbfb8aa3b, v1
	v_exp_f32_e32 v4, v4
	s_nop 0
	v_add_f32_e32 v4, 1.0, v4
	v_rcp_f32_e32 v4, v4
	s_nop 0
	v_mul_f32_e32 v1, v1, v4
	v_mul_f32_e32 v4, v0, v1
	v_mov_b32_e32 v0, v2
	v_mov_b32_e32 v1, v6
	v_pk_mul_f32 v[0:1], v[0:1], v[16:17] op_sel_hi:[1,0]
	v_mov_b32_e32 v6, v3
	v_mul_f32_e32 v2, 0xbfb8aa3b, v1
	v_exp_f32_e32 v2, v2
	s_nop 0
	v_add_f32_e32 v2, 1.0, v2
	v_rcp_f32_e32 v2, v2
	s_nop 0
	v_mul_f32_e32 v1, v1, v2
	v_mul_f32_e32 v5, v0, v1
	v_pk_mul_f32 v[0:1], v[6:7], v[16:17] op_sel_hi:[1,0]
	v_add_u32_e32 v6, 0xb0, v144
	v_mul_f32_e32 v2, 0xbfb8aa3b, v1
	v_exp_f32_e32 v2, v2
	s_nop 0
	v_add_f32_e32 v2, 1.0, v2
	v_rcp_f32_e32 v2, v2
	s_nop 0
	v_mul_f32_e32 v1, v1, v2
	v_mul_f32_e32 v3, v0, v1
	v_cvt_pk_bf16_f32 v0, v17, v12
	v_cvt_pk_bf16_f32 v1, v10, v11
	v_cvt_pk_bf16_f32 v2, v8, v4
	v_cvt_pk_bf16_f32 v3, v5, v3
	v_mad_i64_i32 v[4:5], s[4:5], v6, s3, v[112:113]
	v_lshl_add_u64 v[4:5], v[4:5], 0, s[0:1]
	v_lshl_add_u64 v[4:5], v[4:5], 0, s[34:35]
	v_lshl_add_u64 v[4:5], v[4:5], 0, v[184:185]
	s_mov_b64 s[0:1], -1
	global_store_dwordx4 v[4:5], v[0:3], off
	s_cbranch_vccnz .LBB0_31
	s_andn2_b64 vcc, exec, s[8:9]
	s_cbranch_vccnz .LBB0_30
	s_barrier
	s_branch .LBB0_30
